# prep stage 5: sign flips of the -W1 / -U0 tiles folded into the bf16 conversion (neg source modifiers), 16 fewer instructions per item and wave
# speedup vs baseline: 1.0135x; 1.0135x over previous
; __device__ __forceinline__ void st_bf4(bf16_t* p, f32x4 v) { u32x2 u; u.x = pk_bf16(v[0], v[1]); u.y = pk_bf16(v[2], v[3]); *(u32x2*)p = u; }
; #define MFMA16(a, b, c) __builtin_amdgcn_mfma_f32_16x16x32_bf16(a, b, c, 0, 0, 0)
; __device__ __forceinline__ void phase_prep(const Params& p, unsigned char* shm) {
;     ...
;             *(u32x4*)(p.VKG + chbase + crow * 64 + cseg) = *(const u32x4*)(VKt + crow * LD + cseg);
;             *(u32x4*)(p.YVG + chbase + crow * 64 + cseg) = *(const u32x4*)(YVt + crow * LD + cseg);
; #pragma unroll
;             for (int i = 0; i < 4; ++i) {
;                 const int idx = wid + 8 * i; f32x4 c = (f32x4){0.f, 0.f, 0.f, 0.f};
;                 if (idx < 16) { const int mk = idx >> 2, nt = idx & 3;
;                     c = MFMA16(ldfrag(KKtT, LD, 16 * mk, 0, fr, fq), ldfrag(Tm, LD, 16 * nt, 0, fr, fq), c);
;                     c = MFMA16(ldfrag(KKtT, LD, 16 * mk, 32, fr, fq), ldfrag(Tm, LD, 16 * nt, 32, fr, fq), c);
;                     st_bf4(W1t + (16 * nt + fr) * LD + 16 * mk + 4 * fq, -c);
;                 } else { const int i2 = idx - 16, mt = i2 >> 2, nv = i2 & 3;
;                     c = MFMA16(ldfrag(Tm, LD, 16 * mt, 0, fr, fq), ldfrag(XT, LD, 16 * nv, 0, fr, fq), c);
;                     c = MFMA16(ldfrag(Tm, LD, 16 * mt, 32, fr, fq), ldfrag(XT, LD, 16 * nv, 32, fr, fq), c);
;                     st_bf4(U0t + (16 * nv + fr) * LD + 16 * mt + 4 * fq, -c);
;                 }
;             }
.LBB0_256:
	s_mov_b64 s[20:21], s[98:99]
	s_mov_b64 s[22:23], s[100:101]
	v_mul_lo_u32 v24, v186, s54
	v_lshlrev_b32_e32 v26, 1, v24
	v_add3_u32 v24, 0, v26, v144
	ds_read_b128 v[28:31], v24 offset:26624
	s_lshl_b64 s[18:19], s[44:45], 1
	v_lshlrev_b32_e32 v24, 6, v186
	s_waitcnt lgkmcnt(0)
	s_add_u32 s22, s22, s18
	v_ashrrev_i32_e32 v25, 31, v24
	s_addc_u32 s23, s23, s19
	v_lshlrev_b64 v[24:25], 1, v[24:25]
	v_lshl_add_u64 v[32:33], s[22:23], 0, v[24:25]
	v_mov_b32_e32 v145, v127
	v_add3_u32 v27, s57, v26, v144
	v_lshl_add_u64 v[36:37], v[32:33], 0, v[144:145]
	ds_read_b128 v[32:35], v27
	s_add_u32 s20, s20, s18
	s_addc_u32 s21, s21, s19
	global_store_dwordx4 v[36:37], v[28:31], off
	v_and_or_b32 v27, s72, 48, v185
	s_lshl_b32 s22, s71, 2
	v_lshl_add_u64 v[28:29], s[20:21], 0, v[24:25]
	v_lshl_add_u64 v[28:29], v[28:29], 0, v[144:145]
	s_waitcnt lgkmcnt(0)
	global_store_dwordx4 v[28:29], v[32:35], off
	v_mul_u32_u24_e32 v29, 0x90, v27
	v_add3_u32 v27, 0, v29, v40
	v_add3_u32 v28, s56, v29, v41
	s_cmp_gt_i32 s71, 15
	s_mov_b64 s[20:21], -1
	s_cbranch_scc0 .LBB0_264
	s_and_b32 s20, s22, 0x7ffffff0
	s_sub_i32 s20, s20, 64
	v_or_b32_e32 v30, s20, v185
	v_mul_lo_u32 v30, v30, s50
	v_add3_u32 v34, 0, v30, v40
	ds_read_b128 v[30:33], v34 offset:17408
	ds_read_b128 v[34:37], v34 offset:17472
	ds_read_b128 v[42:45], v27 offset:64512
	ds_read_b128 v[46:49], v27 offset:64576
	v_lshl_add_u32 v38, s20, 1, v28
	s_waitcnt lgkmcnt(1)
	v_mfma_f32_16x16x32_bf16 v[30:33], v[30:33], v[42:45], 0
	s_waitcnt lgkmcnt(0)
	v_mfma_f32_16x16x32_bf16 v[30:33], v[34:37], v[46:49], v[30:33]
	s_nop 7
	v_cvt_pk_bf16_f32 v30, -v30, -v31
	v_cvt_pk_bf16_f32 v31, -v32, -v33
	ds_write_b64 v38, v[30:31]
	v_add3_u32 v29, s58, v29, v41
	s_cbranch_execz .LBB0_265

; __device__ __forceinline__ void st_bf4(bf16_t* p, f32x4 v) { u32x2 u; u.x = pk_bf16(v[0], v[1]); u.y = pk_bf16(v[2], v[3]); *(u32x2*)p = u; }
; #define MFMA16(a, b, c) __builtin_amdgcn_mfma_f32_16x16x32_bf16(a, b, c, 0, 0, 0)
; __device__ __forceinline__ void phase_prep(const Params& p, unsigned char* shm) {
;     ...
;                 } else { const int i2 = idx - 16, mt = i2 >> 2, nv = i2 & 3;
;                     c = MFMA16(ldfrag(Tm, LD, 16 * mt, 0, fr, fq), ldfrag(XT, LD, 16 * nv, 0, fr, fq), c);
;                     c = MFMA16(ldfrag(Tm, LD, 16 * mt, 32, fr, fq), ldfrag(XT, LD, 16 * nv, 32, fr, fq), c);
;                     st_bf4(U0t + (16 * nv + fr) * LD + 16 * mt + 4 * fq, -c);
.LBB0_259:
	s_and_b32 s20, s23, 0x7ffffff0
	s_sub_i32 s20, s20, 64
	v_or_b32_e32 v30, s20, v185
	v_mul_lo_u32 v30, v30, s50
	v_add3_u32 v34, 0, v30, v40
	ds_read_b128 v[30:33], v34 offset:17408
	ds_read_b128 v[34:37], v34 offset:17472
	ds_read_b128 v[42:45], v27 offset:64512
	ds_read_b128 v[46:49], v27 offset:64576
	v_lshl_add_u32 v38, s20, 1, v28
	s_waitcnt lgkmcnt(1)
	v_mfma_f32_16x16x32_bf16 v[30:33], v[30:33], v[42:45], 0
	s_waitcnt lgkmcnt(0)
	v_mfma_f32_16x16x32_bf16 v[30:33], v[34:37], v[46:49], v[30:33]
	s_nop 7
	v_cvt_pk_bf16_f32 v30, -v30, -v31
	v_cvt_pk_bf16_f32 v31, -v32, -v33
	ds_write_b64 v38, v[30:31]
	s_cbranch_execz .LBB0_267

; __device__ __forceinline__ void st_bf4(bf16_t* p, f32x4 v) { u32x2 u; u.x = pk_bf16(v[0], v[1]); u.y = pk_bf16(v[2], v[3]); *(u32x2*)p = u; }
; #define MFMA16(a, b, c) __builtin_amdgcn_mfma_f32_16x16x32_bf16(a, b, c, 0, 0, 0)
; __device__ __forceinline__ void phase_prep(const Params& p, unsigned char* shm) {
;     ...
;                 } else { const int i2 = idx - 16, mt = i2 >> 2, nv = i2 & 3;
;                     c = MFMA16(ldfrag(Tm, LD, 16 * mt, 0, fr, fq), ldfrag(XT, LD, 16 * nv, 0, fr, fq), c);
;                     c = MFMA16(ldfrag(Tm, LD, 16 * mt, 32, fr, fq), ldfrag(XT, LD, 16 * nv, 32, fr, fq), c);
;                     st_bf4(U0t + (16 * nv + fr) * LD + 16 * mt + 4 * fq, -c);
.LBB0_263:
	s_and_b32 s20, s22, 0x7ffffff0
	s_sub_i32 s20, s20, 64
	v_or_b32_e32 v30, s20, v185
	v_mul_lo_u32 v30, v30, s50
	v_add3_u32 v34, 0, v30, v40
	ds_read_b128 v[30:33], v34 offset:17408
	ds_read_b128 v[34:37], v34 offset:17472
	ds_read_b128 v[42:45], v27 offset:64512
	ds_read_b128 v[46:49], v27 offset:64576
	v_lshl_add_u32 v28, s20, 1, v28
	s_waitcnt lgkmcnt(1)
	v_mfma_f32_16x16x32_bf16 v[30:33], v[30:33], v[42:45], 0
	s_waitcnt lgkmcnt(0)
	v_mfma_f32_16x16x32_bf16 v[30:33], v[34:37], v[46:49], v[30:33]
	s_nop 7
	v_cvt_pk_bf16_f32 v30, -v30, -v31
	v_cvt_pk_bf16_f32 v31, -v32, -v33
	ds_write_b64 v28, v[30:31]
	s_cbranch_execnz .LBB0_177
	s_branch .LBB0_271

; __device__ __forceinline__ void st_bf4(bf16_t* p, f32x4 v) { u32x2 u; u.x = pk_bf16(v[0], v[1]); u.y = pk_bf16(v[2], v[3]); *(u32x2*)p = u; }
; #define MFMA16(a, b, c) __builtin_amdgcn_mfma_f32_16x16x32_bf16(a, b, c, 0, 0, 0)
; __device__ __forceinline__ void phase_prep(const Params& p, unsigned char* shm) {
;     ...
;                 if (idx < 16) { const int mk = idx >> 2, nt = idx & 3;
;                     c = MFMA16(ldfrag(KKtT, LD, 16 * mk, 0, fr, fq), ldfrag(Tm, LD, 16 * nt, 0, fr, fq), c);
;                     c = MFMA16(ldfrag(KKtT, LD, 16 * mk, 32, fr, fq), ldfrag(Tm, LD, 16 * nt, 32, fr, fq), c);
;                     st_bf4(W1t + (16 * nt + fr) * LD + 16 * mk + 4 * fq, -c);
.LBB0_265:
	s_and_b32 s20, s22, -16
	v_or_b32_e32 v30, s20, v185
	v_mul_lo_u32 v30, v30, s50
	v_add3_u32 v34, s55, v30, v40
	ds_read_b128 v[30:33], v34
	ds_read_b128 v[34:37], v34 offset:64
	ds_read_b128 v[42:45], v27 offset:17408
	ds_read_b128 v[46:49], v27 offset:17472
	v_lshl_add_u32 v38, s20, 1, v29
	s_waitcnt lgkmcnt(1)
	v_mfma_f32_16x16x32_bf16 v[30:33], v[30:33], v[42:45], 0
	s_waitcnt lgkmcnt(0)
	v_mfma_f32_16x16x32_bf16 v[30:33], v[34:37], v[46:49], v[30:33]
	s_nop 7
	v_cvt_pk_bf16_f32 v30, -v30, -v31
	v_cvt_pk_bf16_f32 v31, -v32, -v33
	ds_write_b64 v38, v[30:31]
	s_add_i32 s23, s22, 32
	s_cmp_lt_i32 s71, 8
	s_mov_b64 s[20:21], -1
	s_cbranch_scc0 .LBB0_259

; __device__ __forceinline__ void st_bf4(bf16_t* p, f32x4 v) { u32x2 u; u.x = pk_bf16(v[0], v[1]); u.y = pk_bf16(v[2], v[3]); *(u32x2*)p = u; }
; #define MFMA16(a, b, c) __builtin_amdgcn_mfma_f32_16x16x32_bf16(a, b, c, 0, 0, 0)
; __device__ __forceinline__ void phase_prep(const Params& p, unsigned char* shm) {
;     ...
;                 if (idx < 16) { const int mk = idx >> 2, nt = idx & 3;
;                     c = MFMA16(ldfrag(KKtT, LD, 16 * mk, 0, fr, fq), ldfrag(Tm, LD, 16 * nt, 0, fr, fq), c);
;                     c = MFMA16(ldfrag(KKtT, LD, 16 * mk, 32, fr, fq), ldfrag(Tm, LD, 16 * nt, 32, fr, fq), c);
;                     st_bf4(W1t + (16 * nt + fr) * LD + 16 * mk + 4 * fq, -c);
.LBB0_267:
	s_and_b32 s20, s23, -16
	v_or_b32_e32 v30, s20, v185
	v_mul_lo_u32 v30, v30, s50
	v_add3_u32 v34, s55, v30, v40
	ds_read_b128 v[30:33], v34
	ds_read_b128 v[34:37], v34 offset:64
	ds_read_b128 v[42:45], v27 offset:17408
	ds_read_b128 v[46:49], v27 offset:17472
	v_lshl_add_u32 v38, s20, 1, v29
	s_waitcnt lgkmcnt(1)
	v_mfma_f32_16x16x32_bf16 v[30:33], v[30:33], v[42:45], 0
	s_waitcnt lgkmcnt(0)
	v_mfma_f32_16x16x32_bf16 v[30:33], v[34:37], v[46:49], v[30:33]
	s_nop 7
	v_cvt_pk_bf16_f32 v30, -v30, -v31
	v_cvt_pk_bf16_f32 v31, -v32, -v33
	ds_write_b64 v38, v[30:31]
	s_add_i32 s23, s22, 64
	s_cmp_lt_i32 s71, 0
	s_mov_b64 s[20:21], -1
	s_cbranch_scc0 .LBB0_261

; __device__ __forceinline__ void st_bf4(bf16_t* p, f32x4 v) { u32x2 u; u.x = pk_bf16(v[0], v[1]); u.y = pk_bf16(v[2], v[3]); *(u32x2*)p = u; }
; #define MFMA16(a, b, c) __builtin_amdgcn_mfma_f32_16x16x32_bf16(a, b, c, 0, 0, 0)
; __device__ __forceinline__ void phase_prep(const Params& p, unsigned char* shm) {
;     ...
;                 if (idx < 16) { const int mk = idx >> 2, nt = idx & 3;
;                     c = MFMA16(ldfrag(KKtT, LD, 16 * mk, 0, fr, fq), ldfrag(Tm, LD, 16 * nt, 0, fr, fq), c);
;                     c = MFMA16(ldfrag(KKtT, LD, 16 * mk, 32, fr, fq), ldfrag(Tm, LD, 16 * nt, 32, fr, fq), c);
;                     st_bf4(W1t + (16 * nt + fr) * LD + 16 * mk + 4 * fq, -c);
.LBB0_269:
	s_and_b32 s20, s23, -16
	v_or_b32_e32 v30, s20, v185
	v_mul_lo_u32 v30, v30, s50
	v_add3_u32 v34, s55, v30, v40
	ds_read_b128 v[30:33], v34
	ds_read_b128 v[34:37], v34 offset:64
	ds_read_b128 v[42:45], v27 offset:17408
	ds_read_b128 v[46:49], v27 offset:17472
	v_lshl_add_u32 v38, s20, 1, v29
	s_waitcnt lgkmcnt(1)
	v_mfma_f32_16x16x32_bf16 v[30:33], v[30:33], v[42:45], 0
	s_waitcnt lgkmcnt(0)
	v_mfma_f32_16x16x32_bf16 v[30:33], v[34:37], v[46:49], v[30:33]
	s_nop 7
	v_cvt_pk_bf16_f32 v30, -v30, -v31
	v_cvt_pk_bf16_f32 v31, -v32, -v33
	ds_write_b64 v38, v[30:31]
	s_addk_i32 s22, 0x60
	s_cmp_lt_i32 s71, -8
	s_mov_b64 s[20:21], -1
	s_cbranch_scc0 .LBB0_263

; __device__ __forceinline__ void st_bf4(bf16_t* p, f32x4 v) { u32x2 u; u.x = pk_bf16(v[0], v[1]); u.y = pk_bf16(v[2], v[3]); *(u32x2*)p = u; }
; #define MFMA16(a, b, c) __builtin_amdgcn_mfma_f32_16x16x32_bf16(a, b, c, 0, 0, 0)
; __device__ __forceinline__ void phase_prep(const Params& p, unsigned char* shm) {
;     ...
;                 if (idx < 16) { const int mk = idx >> 2, nt = idx & 3;
;                     c = MFMA16(ldfrag(KKtT, LD, 16 * mk, 0, fr, fq), ldfrag(Tm, LD, 16 * nt, 0, fr, fq), c);
;                     c = MFMA16(ldfrag(KKtT, LD, 16 * mk, 32, fr, fq), ldfrag(Tm, LD, 16 * nt, 32, fr, fq), c);
;                     st_bf4(W1t + (16 * nt + fr) * LD + 16 * mk + 4 * fq, -c);
.LBB0_271:
	s_and_b32 s20, s22, -16
	v_or_b32_e32 v28, s20, v185
	v_mul_lo_u32 v28, v28, s50
	v_add3_u32 v28, s55, v28, v40
	ds_read_b128 v[30:33], v28
	ds_read_b128 v[34:37], v28 offset:64
	ds_read_b128 v[38:41], v27 offset:17408
	ds_read_b128 v[42:45], v27 offset:17472
	v_lshl_add_u32 v27, s20, 1, v29
	s_waitcnt lgkmcnt(1)
	v_mfma_f32_16x16x32_bf16 v[30:33], v[30:33], v[38:41], 0
	s_waitcnt lgkmcnt(0)
	v_mfma_f32_16x16x32_bf16 v[28:31], v[34:37], v[42:45], v[30:33]
	s_nop 7
	v_cvt_pk_bf16_f32 v28, -v28, -v29
	v_cvt_pk_bf16_f32 v29, -v30, -v31
	ds_write_b64 v27, v[28:29]
	s_branch .LBB0_177
